# P10 items remapped so the four waves of a block (and both blocks of a CU) work on the same PEER head and share sub-key fragments in L1
# speedup vs baseline: 1.1646x; 1.0004x over previous
; #define REP(ph) for (int rp_ = 0; rp_ < ((DBL == (ph)) ? 2 : 1); ++rp_)
; DI void peer_topk_wave(const Params& p, int item, unsigned* lds  ) {
;   const int lane = threadIdx.x & 63, r = lane & 15, kg = lane >> 4;
;   const int h = item & 7, row0 = (item >> 3) * 16;
; __global__ void __launch_bounds__(256, 2) mega(Params pk) {
;     ...
;   REP(10) {
;     unsigned* lds = (unsigned*)smem + w * 512;
;     for (int it = blockIdx.x * 4 + w; it < 2056 * 8; it += gridDim.x * 4) peer_topk_wave(p, it, lds);
.LBB0_1087:
	s_or_b64 exec, exec, s[2:3]
	s_movk_i32 s0, 0x4040
	v_cmp_gt_i32_e32 vcc, s0, v163
	s_waitcnt lgkmcnt(0)
	s_barrier
	s_and_saveexec_b64 s[72:73], vcc
	s_cbranch_execz .LBB0_1304
	v_mov_b32_e32 v3, 0x61
	v_cmp_eq_u32_e64 s[10:11], 2, v175
	v_mov_b32_e32 v5, 0x42
	v_lshlrev_b32_e32 v1, 7, v134
	v_cndmask_b32_e64 v97, v3, 32, s[10:11]
	v_mov_b32_e32 v3, 0x70
	v_cndmask_b32_e64 v98, v3, 33, s[10:11]
	v_mov_b32_e32 v3, 0x71
	v_cndmask_b32_e64 v99, v3, 34, s[10:11]
	v_mov_b32_e32 v3, 0x80
	v_cndmask_b32_e64 v100, v3, 35, s[10:11]
	v_mov_b32_e32 v3, 0x90
	v_cndmask_b32_e64 v101, v3, 36, s[10:11]
	v_mov_b32_e32 v3, 0xa0
	v_cndmask_b32_e64 v102, v3, 48, s[10:11]
	v_mov_b32_e32 v3, 0xb0
	v_cndmask_b32_e64 v103, v3, 49, s[10:11]
	v_mov_b32_e32 v3, 0xc0
	v_cndmask_b32_e64 v104, v3, 50, s[10:11]
	v_mov_b32_e32 v3, 0xd0
	v_cndmask_b32_e64 v105, v3, 51, s[10:11]
	v_mov_b32_e32 v3, 0xe0
	v_cndmask_b32_e64 v106, v3, v5, s[10:11]
	v_mov_b32_e32 v3, 0xf0
	v_mov_b32_e32 v5, 0x50
	v_cndmask_b32_e64 v107, v3, v5, s[10:11]
	v_mov_b32_e32 v3, 0x51
	v_cndmask_b32_e64 v108, 0, v3, s[10:11]
	v_mov_b32_e32 v3, 0x60
	v_cndmask_b32_e64 v109, 0, v3, s[10:11]
	v_lshlrev_b32_e32 v3, 11, v174
	v_add_u32_e32 v110, v3, v1
	v_and_b32_e32 v3, 64, v128
	v_or_b32_e32 v0, v171, v1
	v_xor_b32_e32 v1, 16, v128
	v_add_u32_e32 v3, 64, v3
	v_cmp_lt_i32_e32 vcc, v1, v3
	v_mov_b32_e32 v17, 0
	v_or_b32_e32 v2, 32, v0
	v_cndmask_b32_e32 v1, v128, v1, vcc
	v_lshlrev_b32_e32 v111, 2, v1
	v_xor_b32_e32 v1, 32, v128
	v_cmp_lt_i32_e32 vcc, v1, v3
	v_or_b32_e32 v4, 64, v0
	v_or_b32_e32 v6, 0x60, v0
	v_cndmask_b32_e32 v1, v128, v1, vcc
	v_or_b32_e32 v8, 0x800, v0
	v_or_b32_e32 v10, 0x820, v0
	v_or_b32_e32 v12, 0x840, v0
	v_or_b32_e32 v14, 0x860, v0
	v_or_b32_e32 v16, 0x1000, v0
	v_or_b32_e32 v32, 0x1020, v0
	v_or_b32_e32 v34, 0x1040, v0
	v_or_b32_e32 v36, 0x1060, v0
	v_or_b32_e32 v38, 0x1800, v0
	v_or_b32_e32 v40, 0x1820, v0
	v_or_b32_e32 v42, 0x1840, v0
	v_or_b32_e32 v44, 0x1860, v0
	v_or_b32_e32 v46, 0x2000, v0
	v_or_b32_e32 v48, 0x2020, v0
	v_or_b32_e32 v50, 0x2040, v0
	v_or_b32_e32 v52, 0x2060, v0
	v_or_b32_e32 v54, 0x2800, v0
	v_or_b32_e32 v56, 0x2820, v0
	v_or_b32_e32 v58, 0x2840, v0
	v_or_b32_e32 v60, 0x2860, v0
	v_or_b32_e32 v62, 0x3000, v0
	v_or_b32_e32 v64, 0x3020, v0
	v_or_b32_e32 v66, 0x3040, v0
	v_or_b32_e32 v68, 0x3060, v0
	v_or_b32_e32 v70, 0x3800, v0
	v_or_b32_e32 v72, 0x3820, v0
	v_or_b32_e32 v74, 0x3840, v0
	v_or_b32_e32 v76, 0x3860, v0
	v_lshlrev_b32_e32 v112, 2, v1
	v_lshlrev_b32_e32 v1, 1, v174
	v_or_b32_e32 v90, 16, v170
	v_or_b32_e32 v91, 32, v170
	v_or_b32_e32 v92, 48, v170
	v_or_b32_e32 v93, 64, v170
	v_or_b32_e32 v94, 0x50, v170
	v_or_b32_e32 v95, 0x60, v170
	v_or_b32_e32 v96, 0x70, v170
	v_cmp_gt_u32_e64 s[4:5], 2, v175
	v_cmp_eq_u32_e64 s[12:13], 3, v175
	v_or_b32_e32 v113, 1, v170
	v_or_b32_e32 v114, 2, v170
	v_or_b32_e32 v115, 3, v170
	v_or_b32_e32 v116, 17, v170
	v_or_b32_e32 v117, 18, v170
	v_or_b32_e32 v118, 19, v170
	v_or_b32_e32 v119, 33, v170
	v_or_b32_e32 v120, 34, v170
	v_or_b32_e32 v121, 35, v170
	v_or_b32_e32 v122, 49, v170
	v_or_b32_e32 v123, 50, v170
	v_or_b32_e32 v124, 51, v170
	v_or_b32_e32 v125, 0x41, v170
	v_or_b32_e32 v126, 0x42, v170
	v_or_b32_e32 v127, 0x43, v170
	v_or_b32_e32 v129, 0x51, v170
	v_or_b32_e32 v130, 0x52, v170
	v_or_b32_e32 v131, 0x53, v170
	v_or_b32_e32 v135, 0x61, v170
	v_or_b32_e32 v136, 0x62, v170
	v_or_b32_e32 v137, 0x63, v170
	v_or_b32_e32 v138, 0x71, v170
	v_or_b32_e32 v139, 0x72, v170
	v_or_b32_e32 v140, 0x73, v170
	s_lshr_b32 s89, s86, 3
	s_lshl_b32 s89, s89, 2
	v_add_u32_e32 v141, s89, v174
	v_lshlrev_b32_e32 v141, 3, v141
	s_and_b32 s89, s86, 7
	v_or_b32_e32 v141, s89, v141
	v_mov_b32_e32 v238, v141
	v_lshlrev_b32_e32 v141, 1, v141
	s_lshl_b32 s79, s84, 3
	s_mov_b64 s[74:75], 0
	s_mov_b32 s88, 0
	s_mov_b64 s[90:91], 0x1000000
	v_mov_b32_e32 v142, 0x10178
	v_lshlrev_b32_e32 v18, 1, v171
	v_mov_b32_e32 v19, v17
	v_mov_b32_e32 v143, 0x10110
	v_lshlrev_b32_e32 v20, 1, v0
	v_mov_b32_e32 v21, v17
	s_movk_i32 s80, 0xff80
	v_lshlrev_b32_e32 v22, 1, v8
	v_mov_b32_e32 v23, v17
	v_lshlrev_b32_e32 v24, 1, v10
	v_mov_b32_e32 v25, v17
	v_lshlrev_b32_e32 v26, 1, v12
	v_mov_b32_e32 v27, v17
	v_lshlrev_b32_e32 v28, 1, v14
	v_mov_b32_e32 v29, v17
	v_lshlrev_b32_e32 v30, 1, v16
	v_mov_b32_e32 v31, v17
	v_lshlrev_b32_e32 v32, 1, v32
	v_mov_b32_e32 v33, v17
	v_lshlrev_b32_e32 v34, 1, v34
	v_mov_b32_e32 v35, v17
	v_lshlrev_b32_e32 v36, 1, v36
	v_mov_b32_e32 v37, v17
	v_lshlrev_b32_e32 v38, 1, v38
	v_mov_b32_e32 v39, v17
	v_lshlrev_b32_e32 v40, 1, v40
	v_mov_b32_e32 v41, v17
	v_lshlrev_b32_e32 v42, 1, v42
	v_mov_b32_e32 v43, v17
	v_lshlrev_b32_e32 v44, 1, v44
	v_mov_b32_e32 v45, v17
	v_lshlrev_b32_e32 v46, 1, v46
	v_mov_b32_e32 v47, v17
	v_lshlrev_b32_e32 v48, 1, v48
	v_mov_b32_e32 v49, v17
	v_lshlrev_b32_e32 v50, 1, v50
	v_mov_b32_e32 v51, v17
	v_lshlrev_b32_e32 v52, 1, v52
	v_mov_b32_e32 v53, v17
	v_lshlrev_b32_e32 v54, 1, v54
	v_mov_b32_e32 v55, v17
	v_lshlrev_b32_e32 v56, 1, v56
	v_mov_b32_e32 v57, v17
	v_lshlrev_b32_e32 v58, 1, v58
	v_mov_b32_e32 v59, v17
	v_lshlrev_b32_e32 v60, 1, v60
	v_mov_b32_e32 v61, v17
	v_lshlrev_b32_e32 v62, 1, v62
	v_mov_b32_e32 v63, v17
	v_lshlrev_b32_e32 v64, 1, v64
	v_mov_b32_e32 v65, v17
	v_lshlrev_b32_e32 v66, 1, v66
	v_mov_b32_e32 v67, v17
	v_lshlrev_b32_e32 v68, 1, v68
	v_mov_b32_e32 v69, v17
	v_lshlrev_b32_e32 v70, 1, v70
	v_mov_b32_e32 v71, v17
	v_lshlrev_b32_e32 v72, 1, v72
	v_mov_b32_e32 v73, v17
	v_lshlrev_b32_e32 v74, 1, v74
	v_mov_b32_e32 v75, v17
	v_lshlrev_b32_e32 v76, 1, v76
	v_mov_b32_e32 v77, v17
	s_mov_b64 s[76:77], 0x8000
	v_lshlrev_b32_e32 v78, 1, v2
	v_mov_b32_e32 v79, v17
	v_lshlrev_b32_e32 v80, 1, v4
	v_mov_b32_e32 v81, v17
	v_lshlrev_b32_e32 v82, 1, v6
	v_mov_b32_e32 v83, v17
	s_movk_i32 s81, 0x7f
	s_movk_i32 s82, 0xff00
	s_movk_i32 s83, 0xff
	v_mov_b32_e32 v144, 0x101b0
	s_movk_i32 s86, 0x403f
	v_mov_b32_e32 v145, v238
	s_branch .LBB0_1091
